# v11 + phase 0 silu staging loop flattened (3 loads in flight) + early rope-table loads in the in-proj q/k epilogue
# speedup vs baseline: 1.0270x; 1.0006x over previous
.LBB0_1245:
	v_and_b32_e32 v7, 0xfffffc00, v4
	v_add_u32_e32 v8, v0, v7
	v_ashrrev_i32_e32 v9, 31, v8
	s_waitcnt lgkmcnt(0)
	s_movk_i32 s24, 0x80
	v_lshl_add_u64 v[8:9], v[8:9], 2, s[76:77]
	v_cmp_gt_u32_e32 vcc, s24, v6
	v_cndmask_b32_e32 v9, v9, v3, vcc
	v_cndmask_b32_e32 v8, v8, v2, vcc
	global_load_dword v62, v[8:9], off
	v_add_u32_e32 v63, 0x800, v4
	v_and_b32_e32 v63, 0xfffffc00, v63
	v_add_u32_e32 v64, v0, v63
	v_ashrrev_i32_e32 v65, 31, v64
	v_lshl_add_u64 v[64:65], v[64:65], 2, s[76:77]
	global_load_dword v63, v[64:65], off
	v_cmp_gt_u32_e32 vcc, s24, v6
	s_and_saveexec_b64 s[20:21], vcc
	v_add_u32_e32 v66, 0x1000, v4
	v_and_b32_e32 v66, 0xfffffc00, v66
	v_add_u32_e32 v66, v0, v66
	v_ashrrev_i32_e32 v67, 31, v66
	v_lshl_add_u64 v[66:67], v[66:67], 2, s[76:77]
	global_load_dword v66, v[66:67], off
	s_mov_b64 exec, s[20:21]
	s_waitcnt vmcnt(0)
	v_mul_f32_e32 v68, 0xbfb8aa3b, v62
	v_exp_f32_e32 v68, v68
	s_nop 0
	v_add_f32_e32 v69, 1.0, v68
	v_rcp_f32_e32 v68, v69
	s_nop 0
	v_mul_f32_e32 v62, v62, v68
	ds_write_b32 v5, v62
	v_mul_f32_e32 v68, 0xbfb8aa3b, v63
	v_exp_f32_e32 v68, v68
	s_nop 0
	v_add_f32_e32 v69, 1.0, v68
	v_rcp_f32_e32 v68, v69
	s_nop 0
	v_mul_f32_e32 v63, v63, v68
	ds_write_b32 v5, v63 offset:1024
	v_cmp_gt_u32_e32 vcc, s24, v6
	s_and_saveexec_b64 s[20:21], vcc
	v_mul_f32_e32 v68, 0xbfb8aa3b, v66
	v_exp_f32_e32 v68, v68
	s_nop 0
	v_add_f32_e32 v69, 1.0, v68
	v_rcp_f32_e32 v68, v69
	s_nop 0
	v_mul_f32_e32 v66, v66, v68
	ds_write_b32 v5, v66 offset:2048
	s_mov_b64 exec, s[20:21]
	s_movk_i32 s24, 0x17f
